# prompt attention O stores widened (sec 7.3): v_permlane32_swap pairs + dwordx4 stores, 16 -> 8 stores per wave-unit
# speedup vs baseline: 1.0061x; 1.0061x over previous
.LBB0_812:
	s_or_b64 exec, exec, s[52:53]
	s_ashr_i32 s49, s48, 31
	s_lshl_b64 s[48:49], s[48:49], 2
	s_add_u32 s48, s3, s48
	s_addc_u32 s49, s82, s49
	s_waitcnt lgkmcnt(0)
	s_barrier
	global_load_dword v149, v195, s[48:49]
	ds_read_b128 v[2:5], v142
	ds_read_b128 v[6:9], v142 offset:32
	s_waitcnt lgkmcnt(1)
	v_mfma_f32_32x32x16_bf16 v[66:81], v[2:5], v[34:37], 0
	ds_read_b128 v[2:5], v142 offset:64
	v_lshl_add_u64 v[126:127], s[50:51], 1, v[118:119]
	s_and_b64 s[48:49], vcc, s[12:13]
	s_and_b64 s[50:51], vcc, s[14:15]
	s_and_b64 s[52:53], vcc, s[16:17]
	s_and_b64 s[54:55], vcc, s[18:19]
	s_and_b64 s[56:57], vcc, s[20:21]
	s_waitcnt lgkmcnt(1)
	v_mfma_f32_32x32x16_bf16 v[66:81], v[6:9], v[106:109], v[66:81]
	s_and_b64 s[58:59], vcc, s[22:23]
	s_and_b64 s[60:61], vcc, s[24:25]
	s_and_b64 s[62:63], vcc, s[26:27]
	s_and_b64 s[64:65], vcc, s[28:29]
	s_and_b64 s[66:67], vcc, s[30:31]
	s_and_b64 s[68:69], vcc, s[34:35]
	s_and_b64 s[70:71], vcc, s[36:37]
	s_waitcnt lgkmcnt(0)
	v_mfma_f32_32x32x16_bf16 v[66:81], v[2:5], v[102:105], v[66:81]
	ds_read_b128 v[2:5], v142 offset:96
	s_and_b64 s[72:73], vcc, s[38:39]
	s_and_b64 s[74:75], vcc, s[42:43]
	s_and_b64 s[76:77], vcc, s[44:45]
	s_and_b64 s[78:79], vcc, s[0:1]
	s_or_b32 s80, s80, s96
	s_cmp_eq_u32 s80, 0
	s_waitcnt lgkmcnt(0)
	v_mfma_f32_32x32x16_bf16 v[66:81], v[2:5], v[98:101], v[66:81]
	ds_read_b128 v[2:5], v143
	ds_read_b128 v[6:9], v143 offset:32
	s_cselect_b64 s[80:81], -1, 0
	s_mov_b32 s94, 0x3fb8aa3b
	v_or_b32_e32 v152, s97, v150
	s_add_i32 s2, s2, s86
	s_cmpk_lt_i32 s2, 0x200
	s_nop 4
	v_cndmask_b32_e64 v67, v245, v67, s[50:51]
	s_waitcnt lgkmcnt(1)
	v_mfma_f32_32x32x16_bf16 v[50:65], v[2:5], v[34:37], 0
	ds_read_b128 v[2:5], v143 offset:64
	v_cndmask_b32_e64 v68, v245, v68, s[52:53]
	v_cndmask_b32_e64 v69, v245, v69, s[54:55]
	v_cndmask_b32_e64 v70, v245, v70, s[56:57]
	v_cndmask_b32_e64 v71, v245, v71, s[58:59]
	v_cndmask_b32_e64 v72, v245, v72, s[60:61]
	v_cndmask_b32_e64 v75, v245, v75, s[66:67]
	s_waitcnt lgkmcnt(1)
	v_mfma_f32_32x32x16_bf16 v[50:65], v[6:9], v[106:109], v[50:65]
	v_cndmask_b32_e64 v78, v245, v78, s[72:73]
	v_cndmask_b32_e64 v79, v245, v79, s[74:75]
	v_cndmask_b32_e64 v80, v245, v80, s[76:77]
	v_cndmask_b32_e64 v81, v245, v81, s[78:79]
	s_waitcnt vmcnt(0)
	v_mul_f32_e32 v151, 0x3fb8aa3b, v149
	s_waitcnt lgkmcnt(0)
	v_mfma_f32_32x32x16_bf16 v[50:65], v[2:5], v[102:105], v[50:65]
	ds_read_b128 v[2:5], v143 offset:96
	s_waitcnt lgkmcnt(0)
	v_mfma_f32_32x32x16_bf16 v[50:65], v[2:5], v[98:101], v[50:65]
	ds_read_b128 v[2:5], v144
	ds_read_b128 v[6:9], v144 offset:32
	s_waitcnt lgkmcnt(1)
	v_mfma_f32_32x32x16_bf16 v[18:33], v[2:5], v[34:37], 0
	ds_read_b128 v[2:5], v144 offset:64
	s_nop 6
	v_cndmask_b32_e32 v50, v245, v50, vcc
	v_cndmask_b32_e32 v54, v245, v54, vcc
	v_cndmask_b32_e32 v59, v245, v59, vcc
	v_cndmask_b32_e32 v60, v245, v60, vcc
	v_cndmask_b32_e32 v153, v245, v61, vcc
	v_cndmask_b32_e32 v63, v245, v63, vcc
	s_waitcnt lgkmcnt(1)
	v_mfma_f32_32x32x16_bf16 v[18:33], v[6:9], v[106:109], v[18:33]
	v_cndmask_b32_e32 v65, v245, v65, vcc
	s_waitcnt lgkmcnt(0)
	v_mfma_f32_32x32x16_bf16 v[18:33], v[2:5], v[102:105], v[18:33]
	ds_read_b128 v[2:5], v144 offset:96
	s_waitcnt lgkmcnt(0)
	v_mfma_f32_32x32x16_bf16 v[18:33], v[2:5], v[98:101], v[18:33]
	ds_read_b128 v[2:5], v145
	ds_read_b128 v[38:41], v145 offset:32
	s_waitcnt lgkmcnt(1)
	v_mfma_f32_32x32x16_bf16 v[2:17], v[2:5], v[34:37], 0
	s_nop 7
	v_cndmask_b32_e64 v158, v20, v245, s[80:81]
	v_cndmask_b32_e64 v159, v21, v245, s[80:81]
	v_cndmask_b32_e64 v160, v22, v245, s[80:81]
	v_cndmask_b32_e64 v161, v23, v245, s[80:81]
	v_cndmask_b32_e64 v162, v24, v245, s[80:81]
	v_cndmask_b32_e64 v163, v25, v245, s[80:81]
	v_cndmask_b32_e64 v164, v26, v245, s[80:81]
	s_waitcnt lgkmcnt(0)
	v_mfma_f32_32x32x16_bf16 v[2:17], v[38:41], v[106:109], v[2:17]
	ds_read_b128 v[38:41], v145 offset:64
	v_cndmask_b32_e64 v165, v27, v245, s[80:81]
	v_cndmask_b32_e64 v166, v28, v245, s[80:81]
	v_cndmask_b32_e64 v167, v29, v245, s[80:81]
	v_cndmask_b32_e64 v168, v30, v245, s[80:81]
	s_waitcnt lgkmcnt(0)
	v_mfma_f32_32x32x16_bf16 v[2:17], v[38:41], v[102:105], v[2:17]
	ds_read_b128 v[38:41], v145 offset:96
	s_waitcnt lgkmcnt(0)
	v_mfma_f32_32x32x16_bf16 v[2:17], v[38:41], v[98:101], v[2:17]
	ds_read_b128 v[38:41], v146
	ds_read_b128 v[154:157], v146 offset:32
	s_waitcnt lgkmcnt(1)
	v_mfma_f32_32x32x16_bf16 v[34:49], v[38:41], v[34:37], 0
	s_nop 7
	v_cndmask_b32_e64 v61, v5, v245, s[80:81]
	v_cndmask_b32_e64 v30, v14, v245, s[80:81]
	v_cndmask_b32_e64 v29, v15, v245, s[80:81]
	v_cndmask_b32_e64 v28, v16, v245, s[80:81]
	v_cndmask_b32_e64 v27, v17, v245, s[80:81]
	s_waitcnt lgkmcnt(0)
	v_mfma_f32_32x32x16_bf16 v[34:49], v[154:157], v[106:109], v[34:49]
	ds_read_b128 v[106:109], v146 offset:64
	v_cndmask_b32_e32 v154, v245, v62, vcc
	v_cndmask_b32_e32 v155, v245, v64, vcc
	v_cndmask_b32_e64 v156, v18, v245, s[80:81]
	v_cndmask_b32_e64 v157, v19, v245, s[80:81]
	v_cndmask_b32_e64 v64, v4, v245, s[80:81]
	s_waitcnt lgkmcnt(0)
	v_mfma_f32_32x32x16_bf16 v[34:49], v[106:109], v[102:105], v[34:49]
	ds_read_b128 v[102:105], v146 offset:96
	v_cndmask_b32_e32 v106, v245, v55, vcc
	v_cndmask_b32_e32 v107, v245, v56, vcc
	v_cndmask_b32_e32 v108, v245, v57, vcc
	v_cndmask_b32_e32 v109, v245, v58, vcc
	v_cndmask_b32_e64 v58, v6, v245, s[80:81]
	v_cndmask_b32_e64 v57, v7, v245, s[80:81]
	s_waitcnt lgkmcnt(0)
	v_mfma_f32_32x32x16_bf16 v[34:49], v[102:105], v[98:101], v[34:49]
	v_cndmask_b32_e64 v98, v245, v66, s[48:49]
	v_max3_f32 v66, v151, v98, v67
	v_max3_f32 v66, v66, v68, v69
	v_max3_f32 v66, v66, v70, v71
	v_cndmask_b32_e64 v99, v245, v73, s[62:63]
	v_max3_f32 v66, v66, v72, v99
	v_cndmask_b32_e64 v100, v245, v74, s[64:65]
	v_max3_f32 v66, v66, v100, v75
	v_cndmask_b32_e64 v101, v245, v76, s[68:69]
	v_cndmask_b32_e64 v102, v245, v77, s[70:71]
	v_max3_f32 v66, v66, v101, v102
	v_max3_f32 v66, v66, v78, v79
	v_max3_f32 v66, v66, v80, v81
	v_cndmask_b32_e32 v103, v245, v51, vcc
	v_max3_f32 v51, v66, v50, v103
	v_cndmask_b32_e32 v104, v245, v52, vcc
	v_cndmask_b32_e32 v105, v245, v53, vcc
	v_max3_f32 v51, v51, v104, v105
	v_max3_f32 v51, v51, v54, v106
	v_max3_f32 v51, v51, v107, v108
	v_max3_f32 v51, v51, v109, v59
	v_max3_f32 v51, v51, v60, v153
	v_max3_f32 v51, v51, v154, v63
	v_max3_f32 v51, v51, v155, v65
	v_max3_f32 v18, v51, v156, v157
	v_max3_f32 v18, v18, v158, v159
	v_max3_f32 v18, v18, v160, v161
	v_max3_f32 v18, v18, v162, v163
	v_max3_f32 v18, v18, v164, v165
	v_max3_f32 v18, v18, v166, v167
	v_cndmask_b32_e64 v77, v31, v245, s[80:81]
	v_max3_f32 v18, v18, v168, v77
	v_cndmask_b32_e64 v76, v32, v245, s[80:81]
	v_cndmask_b32_e64 v74, v33, v245, s[80:81]
	v_max3_f32 v18, v18, v76, v74
	v_cndmask_b32_e64 v73, v2, v245, s[80:81]
	v_cndmask_b32_e64 v66, v3, v245, s[80:81]
	v_max3_f32 v2, v18, v73, v66
	v_max3_f32 v2, v2, v64, v61
	v_max3_f32 v2, v2, v58, v57
	v_cndmask_b32_e64 v55, v8, v245, s[80:81]
	v_cndmask_b32_e64 v53, v9, v245, s[80:81]
	v_max3_f32 v2, v2, v55, v53
	v_cndmask_b32_e64 v52, v10, v245, s[80:81]
	v_cndmask_b32_e64 v33, v11, v245, s[80:81]
	v_max3_f32 v2, v2, v52, v33
	v_cndmask_b32_e64 v32, v12, v245, s[80:81]
	v_cndmask_b32_e64 v31, v13, v245, s[80:81]
	v_max3_f32 v2, v2, v32, v31
	v_max3_f32 v2, v2, v30, v29
	v_max3_f32 v2, v2, v28, v27
	v_cndmask_b32_e64 v26, v34, v245, s[12:13]
	v_cndmask_b32_e64 v25, v245, v35, s[46:47]
	v_max3_f32 v2, v2, v26, v25
	v_cndmask_b32_e64 v24, v36, v245, s[16:17]
	v_cndmask_b32_e64 v23, v37, v245, s[18:19]
	v_max3_f32 v2, v2, v24, v23
	v_cndmask_b32_e64 v22, v38, v245, s[20:21]
	v_cndmask_b32_e64 v21, v39, v245, s[22:23]
	v_max3_f32 v2, v2, v22, v21
	v_cndmask_b32_e64 v20, v40, v245, s[24:25]
	v_cndmask_b32_e64 v19, v41, v245, s[26:27]
	v_max3_f32 v2, v2, v20, v19
	v_cndmask_b32_e64 v18, v42, v245, s[28:29]
	v_cndmask_b32_e64 v17, v43, v245, s[30:31]
	v_max3_f32 v2, v2, v18, v17
	v_cndmask_b32_e64 v16, v44, v245, s[34:35]
	v_cndmask_b32_e64 v15, v45, v245, s[36:37]
	v_max3_f32 v2, v2, v16, v15
	v_cndmask_b32_e64 v14, v46, v245, s[38:39]
	v_cndmask_b32_e64 v13, v47, v245, s[42:43]
	v_max3_f32 v2, v2, v14, v13
	v_cndmask_b32_e64 v12, v48, v245, s[44:45]
	v_cndmask_b32_e64 v11, v49, v245, s[0:1]
	v_max3_f32 v2, v2, v12, v11
	ds_bpermute_b32 v3, v129, v2
	s_waitcnt lgkmcnt(0)
	v_max_f32_e32 v3, v3, v3
	v_max_f32_e32 v10, v2, v3
	v_sub_f32_e32 v2, v98, v10
	v_exp_f32_e32 v2, v2
	v_sub_f32_e32 v3, v67, v10
	v_exp_f32_e32 v3, v3
	v_sub_f32_e32 v35, v100, v10
	v_add_f32_e32 v4, 0, v2
	v_exp_f32_e32 v35, v35
	v_add_f32_e32 v5, v3, v4
	v_sub_f32_e32 v4, v68, v10
	v_exp_f32_e32 v4, v4
	v_sub_f32_e32 v36, v75, v10
	v_exp_f32_e32 v36, v36
	v_sub_f32_e32 v37, v101, v10
	v_add_f32_e32 v6, v4, v5
	v_sub_f32_e32 v5, v69, v10
	v_exp_f32_e32 v5, v5
	v_exp_f32_e32 v38, v37
	v_sub_f32_e32 v37, v102, v10
	v_exp_f32_e32 v39, v37
	v_add_f32_e32 v7, v5, v6
	v_sub_f32_e32 v6, v70, v10
	v_exp_f32_e32 v6, v6
	v_sub_f32_e32 v37, v78, v10
	v_exp_f32_e32 v40, v37
	v_sub_f32_e32 v37, v79, v10
	v_add_f32_e32 v8, v6, v7
	v_sub_f32_e32 v7, v71, v10
	v_exp_f32_e32 v7, v7
	v_exp_f32_e32 v45, v37
	v_sub_f32_e32 v37, v80, v10
	v_exp_f32_e32 v48, v37
	v_add_f32_e32 v9, v7, v8
	v_sub_f32_e32 v8, v72, v10
	v_exp_f32_e32 v8, v8
	v_sub_f32_e32 v37, v81, v10
	v_exp_f32_e32 v51, v37
	v_sub_f32_e32 v37, v50, v10
	v_add_f32_e32 v34, v8, v9
	v_sub_f32_e32 v9, v99, v10
	v_exp_f32_e32 v9, v9
	v_exp_f32_e32 v37, v37
	v_sub_f32_e32 v41, v103, v10
	v_exp_f32_e32 v41, v41
	v_add_f32_e32 v34, v9, v34
	v_add_f32_e32 v34, v35, v34
	v_add_f32_e32 v34, v36, v34
	v_add_f32_e32 v34, v38, v34
	v_add_f32_e32 v34, v39, v34
	v_add_f32_e32 v34, v40, v34
	v_add_f32_e32 v34, v45, v34
	v_sub_f32_e32 v42, v104, v10
	v_add_f32_e32 v34, v48, v34
	v_exp_f32_e32 v43, v42
	v_sub_f32_e32 v42, v105, v10
	v_add_f32_e32 v34, v51, v34
	v_exp_f32_e32 v44, v42
	v_sub_f32_e32 v42, v54, v10
	v_add_f32_e32 v34, v37, v34
	v_exp_f32_e32 v47, v42
	v_sub_f32_e32 v42, v106, v10
	v_add_f32_e32 v34, v41, v34
	v_exp_f32_e32 v56, v42
	v_sub_f32_e32 v42, v107, v10
	v_add_f32_e32 v34, v43, v34
	v_exp_f32_e32 v62, v42
	v_sub_f32_e32 v42, v108, v10
	v_add_f32_e32 v34, v44, v34
	v_exp_f32_e32 v67, v42
	v_sub_f32_e32 v42, v109, v10
	v_add_f32_e32 v34, v47, v34
	v_exp_f32_e32 v42, v42
	v_sub_f32_e32 v46, v59, v10
	v_add_f32_e32 v34, v56, v34
	v_exp_f32_e32 v46, v46
	v_sub_f32_e32 v49, v60, v10
	v_add_f32_e32 v34, v62, v34
	v_exp_f32_e32 v50, v49
	v_sub_f32_e32 v49, v153, v10
	v_add_f32_e32 v34, v67, v34
	v_exp_f32_e32 v54, v49
	v_sub_f32_e32 v49, v154, v10
	v_add_f32_e32 v34, v42, v34
	v_exp_f32_e32 v59, v49
	v_sub_f32_e32 v49, v63, v10
	v_add_f32_e32 v34, v46, v34
	v_exp_f32_e32 v69, v49
	v_sub_f32_e32 v49, v155, v10
	v_add_f32_e32 v34, v50, v34
	v_exp_f32_e32 v72, v49
	v_sub_f32_e32 v49, v65, v10
	v_add_f32_e32 v34, v54, v34
	v_exp_f32_e32 v78, v49
	v_sub_f32_e32 v49, v156, v10
	v_add_f32_e32 v34, v59, v34
	v_exp_f32_e32 v49, v49
	v_sub_f32_e32 v60, v157, v10
	v_add_f32_e32 v34, v69, v34
	v_exp_f32_e32 v60, v60
	v_sub_f32_e32 v63, v158, v10
	v_add_f32_e32 v34, v72, v34
	v_exp_f32_e32 v65, v63
	v_sub_f32_e32 v63, v159, v10
	v_add_f32_e32 v34, v78, v34
	v_exp_f32_e32 v68, v63
	v_sub_f32_e32 v63, v160, v10
	v_add_f32_e32 v34, v49, v34
	v_exp_f32_e32 v71, v63
	v_sub_f32_e32 v63, v161, v10
	v_add_f32_e32 v34, v60, v34
	v_exp_f32_e32 v98, v63
	v_sub_f32_e32 v63, v162, v10
	v_add_f32_e32 v34, v65, v34
	v_exp_f32_e32 v103, v63
	v_sub_f32_e32 v63, v163, v10
	v_add_f32_e32 v34, v68, v34
	v_exp_f32_e32 v104, v63
	v_sub_f32_e32 v63, v164, v10
	v_add_f32_e32 v34, v71, v34
	v_exp_f32_e32 v63, v63
	v_sub_f32_e32 v70, v165, v10
	v_add_f32_e32 v34, v98, v34
	v_exp_f32_e32 v70, v70
	v_sub_f32_e32 v75, v166, v10
	v_add_f32_e32 v34, v103, v34
	v_exp_f32_e32 v75, v75
	v_sub_f32_e32 v79, v167, v10
	v_add_f32_e32 v34, v104, v34
	v_exp_f32_e32 v80, v79
	v_sub_f32_e32 v79, v168, v10
	v_add_f32_e32 v34, v63, v34
	v_exp_f32_e32 v101, v79
	v_sub_f32_e32 v77, v77, v10
	v_add_f32_e32 v34, v70, v34
	v_exp_f32_e32 v155, v77
	v_sub_f32_e32 v76, v76, v10
	v_add_f32_e32 v34, v75, v34
	v_exp_f32_e32 v159, v76
	v_sub_f32_e32 v74, v74, v10
	v_add_f32_e32 v34, v80, v34
	v_exp_f32_e32 v163, v74
	v_sub_f32_e32 v73, v73, v10
	v_add_f32_e32 v34, v101, v34
	v_exp_f32_e32 v74, v73
	v_sub_f32_e32 v66, v66, v10
	v_add_f32_e32 v34, v155, v34
	v_exp_f32_e32 v102, v66
	v_sub_f32_e32 v64, v64, v10
	v_add_f32_e32 v34, v159, v34
	v_exp_f32_e32 v153, v64
	v_sub_f32_e32 v61, v61, v10
	v_add_f32_e32 v34, v163, v34
	v_exp_f32_e32 v154, v61
	v_sub_f32_e32 v58, v58, v10
	v_add_f32_e32 v34, v74, v34
	v_exp_f32_e32 v157, v58
	v_sub_f32_e32 v57, v57, v10
	v_add_f32_e32 v34, v102, v34
	v_exp_f32_e32 v166, v57
	v_sub_f32_e32 v55, v55, v10
	v_add_f32_e32 v34, v153, v34
	v_exp_f32_e32 v167, v55
	v_sub_f32_e32 v53, v53, v10
	v_add_f32_e32 v34, v154, v34
	v_exp_f32_e32 v168, v53
	v_sub_f32_e32 v52, v52, v10
	v_add_f32_e32 v34, v157, v34
	v_exp_f32_e32 v109, v52
	v_sub_f32_e32 v33, v33, v10
	v_add_f32_e32 v34, v166, v34
	v_exp_f32_e32 v156, v33
	v_sub_f32_e32 v32, v32, v10
	v_add_f32_e32 v34, v167, v34
	v_exp_f32_e32 v158, v32
	v_sub_f32_e32 v31, v31, v10
	v_add_f32_e32 v34, v168, v34
	v_exp_f32_e32 v160, v31
	v_sub_f32_e32 v30, v30, v10
	v_add_f32_e32 v34, v109, v34
	v_exp_f32_e32 v161, v30
	v_sub_f32_e32 v29, v29, v10
	v_add_f32_e32 v33, v156, v34
	v_exp_f32_e32 v162, v29
	v_sub_f32_e32 v28, v28, v10
	v_add_f32_e32 v32, v158, v33
	v_exp_f32_e32 v164, v28
	v_sub_f32_e32 v27, v27, v10
	v_add_f32_e32 v31, v160, v32
	v_exp_f32_e32 v165, v27
	v_sub_f32_e32 v26, v26, v10
	v_add_f32_e32 v30, v161, v31
	v_exp_f32_e32 v73, v26
	v_sub_f32_e32 v25, v25, v10
	v_add_f32_e32 v29, v162, v30
	v_exp_f32_e32 v76, v25
	v_sub_f32_e32 v24, v24, v10
	v_add_f32_e32 v28, v164, v29
	v_exp_f32_e32 v77, v24
	v_sub_f32_e32 v23, v23, v10
	v_add_f32_e32 v27, v165, v28
	v_exp_f32_e32 v79, v23
	v_sub_f32_e32 v22, v22, v10
	v_add_f32_e32 v26, v73, v27
	v_exp_f32_e32 v81, v22
	v_sub_f32_e32 v21, v21, v10
	v_add_f32_e32 v25, v76, v26
	v_exp_f32_e32 v99, v21
	v_sub_f32_e32 v20, v20, v10
	v_add_f32_e32 v24, v77, v25
	v_exp_f32_e32 v100, v20
	v_sub_f32_e32 v19, v19, v10
	v_add_u32_e32 v105, v130, v131
	v_add_f32_e32 v23, v79, v24
	v_exp_f32_e32 v108, v19
	v_sub_f32_e32 v18, v18, v10
	v_cvt_pk_bf16_f32 v2, v2, v3
	v_cvt_pk_bf16_f32 v3, v4, v5
	v_cvt_pk_bf16_f32 v4, v6, v7
	v_cvt_pk_bf16_f32 v5, v8, v9
	ds_read_b128 v[6:9], v105 offset:36864
	v_add_f32_e32 v22, v81, v23
	v_exp_f32_e32 v52, v18
	v_sub_f32_e32 v17, v17, v10
	v_add_f32_e32 v21, v99, v22
	v_exp_f32_e32 v53, v17
	v_sub_f32_e32 v16, v16, v10
	v_add_f32_e32 v20, v100, v21
	v_exp_f32_e32 v55, v16
	v_sub_f32_e32 v15, v15, v10
	v_add_f32_e32 v19, v108, v20
	v_exp_f32_e32 v57, v15
	v_sub_f32_e32 v14, v14, v10
	v_add_f32_e32 v18, v52, v19
	v_exp_f32_e32 v58, v14
	v_sub_f32_e32 v13, v13, v10
	v_add_f32_e32 v17, v53, v18
	v_exp_f32_e32 v61, v13
	v_sub_f32_e32 v12, v12, v10
	v_add_f32_e32 v16, v55, v17
	v_exp_f32_e32 v64, v12
	v_sub_f32_e32 v11, v11, v10
	v_add_f32_e32 v15, v57, v16
	v_exp_f32_e32 v66, v11
	v_add_u32_e32 v106, v130, v132
	v_add_f32_e32 v14, v58, v15
	s_waitcnt lgkmcnt(0)
	v_mfma_f32_32x32x16_bf16 v[18:33], v[6:9], v[2:5], 0
	ds_read_b128 v[6:9], v106 offset:36864
	v_cvt_pk_bf16_f32 v170, v35, v36
	v_cvt_pk_bf16_f32 v171, v38, v39
	v_cvt_pk_bf16_f32 v172, v40, v45
	v_cvt_pk_bf16_f32 v173, v48, v51
	ds_read_b128 v[174:177], v105 offset:36896
	v_add_f32_e32 v13, v61, v14
	v_add_f32_e32 v12, v64, v13
	v_add_f32_e32 v11, v66, v12
	ds_bpermute_b32 v12, v129, v11
	v_fma_f32 v10, v149, s94, -v10
	v_exp_f32_e32 v10, v10
	s_waitcnt lgkmcnt(1)
	v_mfma_f32_32x32x16_bf16 v[18:33], v[174:177], v[170:173], v[18:33]
	s_waitcnt lgkmcnt(0)
	v_add_f32_e32 v11, v11, v12
	ds_read_b128 v[174:177], v106 offset:36896
	v_add_f32_e32 v34, v10, v11
	v_add_u32_e32 v107, v133, v131
	v_cvt_pk_bf16_f32 v36, v37, v41
	v_cvt_pk_bf16_f32 v37, v43, v44
	v_cvt_pk_bf16_f32 v38, v47, v56
	v_mfma_f32_32x32x16_bf16 v[2:17], v[6:9], v[2:5], 0
	v_cvt_pk_bf16_f32 v39, v62, v67
	v_add_u32_e32 v106, v133, v132
	v_add_u32_e32 v105, v134, v131
	v_div_scale_f32 v35, vcc, v34, v34, 1.0
	s_waitcnt lgkmcnt(0)
	v_mfma_f32_32x32x16_bf16 v[2:17], v[174:177], v[170:173], v[2:17]
	ds_read_b128 v[178:181], v107 offset:36864
	ds_read_b128 v[182:185], v106 offset:36864
	ds_read_b128 v[186:189], v107 offset:36896
	s_waitcnt lgkmcnt(2)
	v_mfma_f32_32x32x16_bf16 v[18:33], v[178:181], v[36:39], v[18:33]
	ds_read_b128 v[190:193], v106 offset:36896
	s_waitcnt lgkmcnt(2)
	v_mfma_f32_32x32x16_bf16 v[2:17], v[182:185], v[36:39], v[2:17]
	v_cvt_pk_bf16_f32 v36, v42, v46
	v_cvt_pk_bf16_f32 v37, v50, v54
	v_cvt_pk_bf16_f32 v38, v59, v69
	v_cvt_pk_bf16_f32 v39, v72, v78
	ds_read_b128 v[178:181], v105 offset:36864
	s_waitcnt lgkmcnt(2)
	v_mfma_f32_32x32x16_bf16 v[18:33], v[186:189], v[36:39], v[18:33]
	v_add_u32_e32 v194, v134, v132
	ds_read_b128 v[182:185], v194 offset:36864
	s_waitcnt lgkmcnt(2)
	v_mfma_f32_32x32x16_bf16 v[2:17], v[190:193], v[36:39], v[2:17]
	v_cvt_pk_bf16_f32 v36, v49, v60
	v_cvt_pk_bf16_f32 v37, v65, v68
	v_cvt_pk_bf16_f32 v38, v71, v98
	v_cvt_pk_bf16_f32 v39, v103, v104
	v_add_u32_e32 v104, v134, v132
	v_add_u32_e32 v103, v135, v131
	ds_read_b128 v[186:189], v105 offset:36896
	s_waitcnt lgkmcnt(2)
	v_mfma_f32_32x32x16_bf16 v[18:33], v[178:181], v[36:39], v[18:33]
	v_or_b32_e32 v98, s88, v152
	ds_read_b128 v[190:193], v104 offset:36896
	s_waitcnt lgkmcnt(2)
	v_mfma_f32_32x32x16_bf16 v[2:17], v[182:185], v[36:39], v[2:17]
	v_cvt_pk_bf16_f32 v36, v63, v70
	v_cvt_pk_bf16_f32 v37, v75, v80
	v_cvt_pk_bf16_f32 v38, v101, v155
	v_cvt_pk_bf16_f32 v39, v159, v163
	v_add_u32_e32 v101, v136, v131
	ds_read_b128 v[178:181], v103 offset:36864
	s_waitcnt lgkmcnt(2)
	v_mfma_f32_32x32x16_bf16 v[18:33], v[186:189], v[36:39], v[18:33]
	v_add_u32_e32 v202, v135, v132
	ds_read_b128 v[182:185], v202 offset:36864
	s_waitcnt lgkmcnt(2)
	v_mfma_f32_32x32x16_bf16 v[2:17], v[190:193], v[36:39], v[2:17]
	v_cvt_pk_bf16_f32 v36, v74, v102
	v_cvt_pk_bf16_f32 v37, v153, v154
	v_cvt_pk_bf16_f32 v38, v157, v166
	v_cvt_pk_bf16_f32 v39, v167, v168
	v_add_u32_e32 v102, v135, v132
	ds_read_b128 v[186:189], v103 offset:36896
	s_waitcnt lgkmcnt(2)
	v_mfma_f32_32x32x16_bf16 v[18:33], v[178:181], v[36:39], v[18:33]
	ds_read_b128 v[190:193], v102 offset:36896
	s_waitcnt lgkmcnt(2)
	v_mfma_f32_32x32x16_bf16 v[2:17], v[182:185], v[36:39], v[2:17]
	v_cvt_pk_bf16_f32 v36, v109, v156
	v_cvt_pk_bf16_f32 v37, v158, v160
	v_cvt_pk_bf16_f32 v38, v161, v162
	v_cvt_pk_bf16_f32 v39, v164, v165
	ds_read_b128 v[178:181], v101 offset:36864
	s_waitcnt lgkmcnt(2)
	v_mfma_f32_32x32x16_bf16 v[18:33], v[186:189], v[36:39], v[18:33]
	v_add_u32_e32 v203, v136, v132
	ds_read_b128 v[182:185], v203 offset:36864
	s_waitcnt lgkmcnt(2)
	v_mfma_f32_32x32x16_bf16 v[2:17], v[190:193], v[36:39], v[2:17]
	v_cvt_pk_bf16_f32 v36, v73, v76
	v_cvt_pk_bf16_f32 v37, v77, v79
	v_cvt_pk_bf16_f32 v38, v81, v99
	v_cvt_pk_bf16_f32 v39, v100, v108
	v_add_u32_e32 v100, v136, v132
	v_mov_b32_e32 v99, s89
	ds_read_b128 v[186:189], v101 offset:36896
	s_waitcnt lgkmcnt(2)
	v_mfma_f32_32x32x16_bf16 v[18:33], v[178:181], v[36:39], v[18:33]
	ds_read_b128 v[190:193], v100 offset:36896
	s_waitcnt lgkmcnt(2)
	v_mfma_f32_32x32x16_bf16 v[2:17], v[182:185], v[36:39], v[2:17]
	v_cvt_pk_bf16_f32 v36, v52, v53
	v_cvt_pk_bf16_f32 v37, v55, v57
	v_cvt_pk_bf16_f32 v38, v58, v61
	v_cvt_pk_bf16_f32 v39, v64, v66
	s_waitcnt lgkmcnt(1)
	v_mfma_f32_32x32x16_bf16 v[18:33], v[186:189], v[36:39], v[18:33]
	s_waitcnt lgkmcnt(0)
	v_mfma_f32_32x32x16_bf16 v[2:17], v[190:193], v[36:39], v[2:17]
	v_rcp_f32_e32 v36, v35
	s_nop 0
	v_fma_f32 v37, -v35, v36, 1.0
	v_fmac_f32_e32 v36, v37, v36
	v_div_scale_f32 v37, vcc, 1.0, v34, 1.0
	v_mul_f32_e32 v38, v37, v36
	v_fma_f32 v39, -v35, v38, v37
	v_fmac_f32_e32 v38, v39, v36
	v_fma_f32 v35, -v35, v38, v37
	v_div_fmas_f32 v35, v35, v36, v38
	v_div_fixup_f32 v36, v35, v34, 1.0
	v_lshlrev_b64 v[34:35], 11, v[98:99]
	v_bfe_u32 v204, v0, 5, 1
	v_lshl_add_u64 v[34:35], v[126:127], 0, v[34:35]
	v_lshlrev_b32_e32 v204, 3, v204
	v_mov_b32_e32 v205, 0
	v_mul_f32_e32 v18, v18, v36
	v_mul_f32_e32 v19, v19, v36
	v_cvt_pk_bf16_f32 v18, v18, v19
	v_mul_f32_e32 v19, v20, v36
	v_mul_f32_e32 v20, v21, v36
	v_cvt_pk_bf16_f32 v19, v19, v20
	v_mul_f32_e32 v20, v22, v36
	v_mul_f32_e32 v21, v23, v36
	v_cvt_pk_bf16_f32 v20, v20, v21
	v_mul_f32_e32 v21, v24, v36
	v_mul_f32_e32 v22, v25, v36
	v_cvt_pk_bf16_f32 v21, v21, v22
	v_lshl_add_u64 v[34:35], v[34:35], 0, v[204:205]
	v_mul_f32_e32 v26, v26, v36
	v_mul_f32_e32 v27, v27, v36
	v_cvt_pk_bf16_f32 v26, v26, v27
	v_mul_f32_e32 v27, v28, v36
	v_mul_f32_e32 v28, v29, v36
	v_cvt_pk_bf16_f32 v27, v27, v28
	v_mul_f32_e32 v28, v30, v36
	v_mul_f32_e32 v29, v31, v36
	v_cvt_pk_bf16_f32 v28, v28, v29
	v_mul_f32_e32 v29, v32, v36
	v_mul_f32_e32 v30, v33, v36
	v_cvt_pk_bf16_f32 v29, v29, v30
	v_permlane32_swap_b32 v18, v20
	v_permlane32_swap_b32 v19, v21
	global_store_dwordx4 v[34:35], v[18:21], off
	v_permlane32_swap_b32 v26, v28
	v_permlane32_swap_b32 v27, v29
	global_store_dwordx4 v[34:35], v[26:29], off offset:32
	v_mul_f32_e32 v2, v2, v36
	v_mul_f32_e32 v3, v3, v36
	v_cvt_pk_bf16_f32 v2, v2, v3
	v_mul_f32_e32 v3, v4, v36
	v_mul_f32_e32 v4, v5, v36
	v_cvt_pk_bf16_f32 v3, v3, v4
	v_mul_f32_e32 v4, v6, v36
	v_mul_f32_e32 v5, v7, v36
	v_cvt_pk_bf16_f32 v4, v4, v5
	v_mul_f32_e32 v5, v8, v36
	v_mul_f32_e32 v6, v9, v36
	v_cvt_pk_bf16_f32 v5, v5, v6
	v_mul_f32_e32 v10, v10, v36
	v_mul_f32_e32 v11, v11, v36
	v_cvt_pk_bf16_f32 v10, v10, v11
	v_mul_f32_e32 v11, v12, v36
	v_mul_f32_e32 v12, v13, v36
	v_cvt_pk_bf16_f32 v11, v11, v12
	v_mul_f32_e32 v12, v14, v36
	v_mul_f32_e32 v13, v15, v36
	v_cvt_pk_bf16_f32 v12, v12, v13
	v_mul_f32_e32 v13, v16, v36
	v_mul_f32_e32 v14, v17, v36
	v_cvt_pk_bf16_f32 v13, v13, v14
	v_permlane32_swap_b32 v2, v4
	v_permlane32_swap_b32 v3, v5
	global_store_dwordx4 v[34:35], v[2:5], off offset:64
	v_permlane32_swap_b32 v10, v12
	v_permlane32_swap_b32 v11, v13
	global_store_dwordx4 v[34:35], v[10:13], off offset:96
	ds_read_b128 v[2:5], v143
	ds_read_b128 v[6:9], v143 offset:32
	s_waitcnt lgkmcnt(1)
	v_mfma_f32_32x32x16_bf16 v[66:81], v[2:5], v[94:97], 0
	ds_read_b128 v[2:5], v143 offset:64
	v_or_b32_e32 v98, s87, v150
	v_or_b32_e32 v98, s88, v98
	s_waitcnt lgkmcnt(1)
	v_mfma_f32_32x32x16_bf16 v[66:81], v[6:9], v[90:93], v[66:81]
	s_waitcnt lgkmcnt(0)
	v_mfma_f32_32x32x16_bf16 v[66:81], v[2:5], v[86:89], v[66:81]
	ds_read_b128 v[2:5], v143 offset:96
	s_waitcnt lgkmcnt(0)
	v_mfma_f32_32x32x16_bf16 v[66:81], v[2:5], v[82:85], v[66:81]
	ds_read_b128 v[2:5], v144
	ds_read_b128 v[6:9], v144 offset:32
	s_waitcnt lgkmcnt(1)
	v_mfma_f32_32x32x16_bf16 v[34:49], v[2:5], v[94:97], 0
	ds_read_b128 v[2:5], v144 offset:64
	s_nop 6
	v_cndmask_b32_e64 v66, v245, v66, s[48:49]
	v_cndmask_b32_e64 v68, v245, v68, s[52:53]
	v_cndmask_b32_e64 v69, v245, v69, s[54:55]
	v_cndmask_b32_e64 v70, v245, v70, s[56:57]
	v_cndmask_b32_e64 v71, v245, v71, s[58:59]
	v_cndmask_b32_e64 v72, v245, v72, s[60:61]
	s_waitcnt lgkmcnt(1)
	v_mfma_f32_32x32x16_bf16 v[34:49], v[6:9], v[90:93], v[34:49]
	v_cndmask_b32_e64 v73, v245, v73, s[62:63]
	v_cndmask_b32_e64 v74, v245, v74, s[64:65]
	v_cndmask_b32_e64 v75, v245, v75, s[66:67]
	v_cndmask_b32_e64 v76, v245, v76, s[68:69]
	v_cndmask_b32_e64 v77, v245, v77, s[70:71]
	v_cndmask_b32_e64 v78, v245, v78, s[72:73]
	v_cndmask_b32_e64 v79, v245, v79, s[74:75]
	s_waitcnt lgkmcnt(0)
	v_mfma_f32_32x32x16_bf16 v[34:49], v[2:5], v[86:89], v[34:49]
	ds_read_b128 v[2:5], v144 offset:96
	v_cndmask_b32_e64 v80, v245, v80, s[76:77]
	v_cndmask_b32_e64 v81, v245, v81, s[78:79]
	s_waitcnt lgkmcnt(0)
	v_mfma_f32_32x32x16_bf16 v[34:49], v[2:5], v[82:85], v[34:49]
	ds_read_b128 v[2:5], v145
	ds_read_b128 v[6:9], v145 offset:32
	s_waitcnt lgkmcnt(1)
	v_mfma_f32_32x32x16_bf16 v[18:33], v[2:5], v[94:97], 0
	ds_read_b128 v[2:5], v145 offset:64
	s_nop 6
	v_cndmask_b32_e64 v42, v42, v245, s[80:81]
	s_waitcnt lgkmcnt(1)
	v_mfma_f32_32x32x16_bf16 v[18:33], v[6:9], v[90:93], v[18:33]
	s_waitcnt lgkmcnt(0)
	v_mfma_f32_32x32x16_bf16 v[18:33], v[2:5], v[86:89], v[18:33]
	ds_read_b128 v[2:5], v145 offset:96
	s_waitcnt lgkmcnt(0)
	v_mfma_f32_32x32x16_bf16 v[18:33], v[2:5], v[82:85], v[18:33]
	ds_read_b128 v[2:5], v146
	ds_read_b128 v[50:53], v146 offset:32
	s_waitcnt lgkmcnt(1)
	v_mfma_f32_32x32x16_bf16 v[2:17], v[2:5], v[94:97], 0
	s_nop 7
	v_cndmask_b32_e64 v108, v18, v245, s[80:81]
	v_cndmask_b32_e64 v109, v19, v245, s[80:81]
	v_cndmask_b32_e64 v150, v20, v245, s[80:81]
	v_cndmask_b32_e64 v156, v26, v245, s[80:81]
	v_cndmask_b32_e64 v157, v27, v245, s[80:81]
	v_cndmask_b32_e64 v158, v28, v245, s[80:81]
	v_cndmask_b32_e64 v159, v29, v245, s[80:81]
	s_waitcnt lgkmcnt(0)
	v_mfma_f32_32x32x16_bf16 v[2:17], v[50:53], v[90:93], v[2:17]
	ds_read_b128 v[50:53], v146 offset:64
	v_cndmask_b32_e64 v160, v30, v245, s[80:81]
	v_cndmask_b32_e64 v161, v31, v245, s[80:81]
	v_cndmask_b32_e64 v162, v32, v245, s[80:81]
	v_cndmask_b32_e64 v163, v33, v245, s[80:81]
	s_waitcnt lgkmcnt(0)
	v_mfma_f32_32x32x16_bf16 v[2:17], v[50:53], v[86:89], v[2:17]
	ds_read_b128 v[50:53], v146 offset:96
	s_waitcnt lgkmcnt(0)
	v_mfma_f32_32x32x16_bf16 v[2:17], v[50:53], v[82:85], v[2:17]
	ds_read_b128 v[50:53], v147
	ds_read_b128 v[152:155], v147 offset:32
	s_waitcnt lgkmcnt(1)
	v_mfma_f32_32x32x16_bf16 v[50:65], v[50:53], v[94:97], 0
	v_cndmask_b32_e64 v94, v46, v245, s[80:81]
	v_cndmask_b32_e64 v95, v47, v245, s[80:81]
	v_cndmask_b32_e64 v96, v48, v245, s[80:81]
	v_cndmask_b32_e64 v97, v49, v245, s[80:81]
	s_waitcnt lgkmcnt(0)
	v_mfma_f32_32x32x16_bf16 v[50:65], v[152:155], v[90:93], v[50:65]
	ds_read_b128 v[90:93], v147 offset:64
	v_cndmask_b32_e64 v152, v22, v245, s[80:81]
	v_cndmask_b32_e64 v153, v23, v245, s[80:81]
	v_cndmask_b32_e64 v154, v24, v245, s[80:81]
	v_cndmask_b32_e64 v155, v25, v245, s[80:81]
	s_waitcnt lgkmcnt(0)
	v_mfma_f32_32x32x16_bf16 v[50:65], v[90:93], v[86:89], v[50:65]
	ds_read_b128 v[86:89], v147 offset:96
	v_cndmask_b32_e64 v90, v41, v245, s[80:81]
	v_cndmask_b32_e64 v91, v43, v245, s[80:81]
	v_cndmask_b32_e64 v92, v44, v245, s[80:81]
	v_cndmask_b32_e64 v93, v45, v245, s[80:81]
	s_waitcnt lgkmcnt(0)
	v_mfma_f32_32x32x16_bf16 v[50:65], v[86:89], v[82:85], v[50:65]
	v_cndmask_b32_e64 v82, v245, v67, s[50:51]
	v_max3_f32 v67, v151, v66, v82
	v_max3_f32 v67, v67, v68, v69
	v_max3_f32 v67, v67, v70, v71
	v_max3_f32 v67, v67, v72, v73
	v_max3_f32 v67, v67, v74, v75
	v_max3_f32 v67, v67, v76, v77
	v_max3_f32 v67, v67, v78, v79
	v_max3_f32 v67, v67, v80, v81
	v_cndmask_b32_e64 v83, v34, v245, s[80:81]
	v_cndmask_b32_e64 v84, v35, v245, s[80:81]
	v_max3_f32 v34, v67, v83, v84
	v_cndmask_b32_e64 v85, v36, v245, s[80:81]
	v_cndmask_b32_e64 v86, v37, v245, s[80:81]
	v_max3_f32 v34, v34, v85, v86
	v_cndmask_b32_e64 v87, v38, v245, s[80:81]
	v_cndmask_b32_e64 v88, v39, v245, s[80:81]
	v_max3_f32 v34, v34, v87, v88
	v_cndmask_b32_e64 v89, v40, v245, s[80:81]
	v_max3_f32 v34, v34, v89, v90
	v_max3_f32 v34, v34, v42, v91
	v_max3_f32 v34, v34, v92, v93
	v_max3_f32 v34, v34, v94, v95
	v_max3_f32 v34, v34, v96, v97
	v_max3_f32 v18, v34, v108, v109
	v_cndmask_b32_e64 v151, v21, v245, s[80:81]
	v_max3_f32 v18, v18, v150, v151
	v_max3_f32 v18, v18, v152, v153
	v_max3_f32 v18, v18, v154, v155
	v_max3_f32 v18, v18, v156, v157
	v_max3_f32 v18, v18, v158, v159
	v_max3_f32 v18, v18, v160, v161
	v_max3_f32 v18, v18, v162, v163
	v_max3_f32 v18, v18, v2, v3
	v_max3_f32 v18, v18, v4, v5
	v_max3_f32 v18, v18, v6, v7
	v_max3_f32 v18, v18, v8, v9
	v_max3_f32 v18, v18, v10, v11
	v_max3_f32 v18, v18, v12, v13
	v_max3_f32 v18, v18, v14, v15
	v_max3_f32 v18, v18, v16, v17
	v_cndmask_b32_e64 v67, v50, v245, s[12:13]
	v_cndmask_b32_e64 v50, v245, v51, s[46:47]
	v_max3_f32 v18, v18, v67, v50
	v_cndmask_b32_e64 v49, v52, v245, s[16:17]
	v_cndmask_b32_e64 v48, v53, v245, s[18:19]
	v_max3_f32 v18, v18, v49, v48
	v_cndmask_b32_e64 v47, v54, v245, s[20:21]
	v_cndmask_b32_e64 v45, v55, v245, s[22:23]
	v_max3_f32 v18, v18, v47, v45
	v_cndmask_b32_e64 v43, v56, v245, s[24:25]
	v_cndmask_b32_e64 v40, v57, v245, s[26:27]
	v_max3_f32 v18, v18, v43, v40
	v_cndmask_b32_e64 v34, v58, v245, s[28:29]
	v_cndmask_b32_e64 v33, v59, v245, s[30:31]
	v_max3_f32 v18, v18, v34, v33
	v_cndmask_b32_e64 v32, v60, v245, s[34:35]
	v_cndmask_b32_e64 v31, v61, v245, s[36:37]
	v_max3_f32 v18, v18, v32, v31
	v_cndmask_b32_e64 v30, v62, v245, s[38:39]
	v_cndmask_b32_e64 v29, v63, v245, s[42:43]
	v_max3_f32 v18, v18, v30, v29
	v_cndmask_b32_e64 v28, v64, v245, s[44:45]
	v_cndmask_b32_e64 v27, v65, v245, s[0:1]
	v_max3_f32 v18, v18, v28, v27
	ds_bpermute_b32 v19, v129, v18
	s_waitcnt lgkmcnt(0)
	v_max_f32_e32 v19, v19, v19
	v_max_f32_e32 v26, v18, v19
	v_sub_f32_e32 v18, v66, v26
	v_exp_f32_e32 v18, v18
	v_sub_f32_e32 v19, v82, v26
	v_exp_f32_e32 v19, v19
	v_sub_f32_e32 v38, v76, v26
	v_add_f32_e32 v20, 0, v18
	v_exp_f32_e32 v38, v38
	v_add_f32_e32 v21, v19, v20
	v_sub_f32_e32 v20, v68, v26
	v_exp_f32_e32 v20, v20
	v_sub_f32_e32 v39, v77, v26
	v_exp_f32_e32 v39, v39
	v_sub_f32_e32 v41, v78, v26
	v_add_f32_e32 v22, v20, v21
	v_sub_f32_e32 v21, v69, v26
	v_exp_f32_e32 v21, v21
	v_exp_f32_e32 v44, v41
	v_sub_f32_e32 v41, v79, v26
	v_exp_f32_e32 v54, v41
	v_add_f32_e32 v23, v21, v22
	v_sub_f32_e32 v22, v70, v26
	v_exp_f32_e32 v22, v22
	v_sub_f32_e32 v41, v80, v26
	v_exp_f32_e32 v58, v41
	v_sub_f32_e32 v41, v81, v26
	v_add_f32_e32 v24, v22, v23
	v_sub_f32_e32 v23, v71, v26
	v_exp_f32_e32 v23, v23
	v_exp_f32_e32 v60, v41
	v_sub_f32_e32 v53, v87, v26
	v_exp_f32_e32 v56, v53
	v_add_f32_e32 v25, v23, v24
	v_sub_f32_e32 v24, v72, v26
	v_exp_f32_e32 v24, v24
	v_sub_f32_e32 v53, v88, v26
	v_exp_f32_e32 v63, v53
	v_sub_f32_e32 v53, v89, v26
	v_add_f32_e32 v35, v24, v25
	v_sub_f32_e32 v25, v73, v26
	v_exp_f32_e32 v25, v25
	v_exp_f32_e32 v70, v53
	v_sub_f32_e32 v53, v90, v26
	v_sub_f32_e32 v42, v42, v26
	v_add_f32_e32 v36, v25, v35
	v_sub_f32_e32 v35, v74, v26
	v_exp_f32_e32 v35, v35
	v_exp_f32_e32 v42, v42
	v_sub_f32_e32 v55, v92, v26
	v_exp_f32_e32 v57, v55
	v_add_f32_e32 v37, v35, v36
	v_sub_f32_e32 v36, v75, v26
	v_exp_f32_e32 v36, v36
	v_exp_f32_e32 v75, v53
	v_sub_f32_e32 v53, v91, v26
	v_exp_f32_e32 v53, v53
	v_add_f32_e32 v37, v36, v37
	v_add_f32_e32 v37, v38, v37
	v_add_f32_e32 v37, v39, v37
	v_add_f32_e32 v37, v44, v37
	v_add_f32_e32 v37, v54, v37
	v_add_f32_e32 v37, v58, v37
	v_add_f32_e32 v41, v60, v37
	v_sub_f32_e32 v37, v83, v26
	v_exp_f32_e32 v37, v37
	v_sub_f32_e32 v55, v93, v26
	v_exp_f32_e32 v59, v55
	v_sub_f32_e32 v55, v94, v26
	v_add_f32_e32 v46, v37, v41
	v_sub_f32_e32 v41, v84, v26
	v_exp_f32_e32 v41, v41
	v_exp_f32_e32 v66, v55
	v_sub_f32_e32 v55, v95, v26
	v_exp_f32_e32 v78, v55
	v_add_f32_e32 v51, v41, v46
	v_sub_f32_e32 v46, v85, v26
	v_exp_f32_e32 v46, v46
	v_sub_f32_e32 v55, v96, v26
	v_exp_f32_e32 v82, v55
	v_sub_f32_e32 v55, v97, v26
	v_add_f32_e32 v52, v46, v51
	v_sub_f32_e32 v51, v86, v26
	v_exp_f32_e32 v51, v51
	v_exp_f32_e32 v85, v55
	v_sub_f32_e32 v55, v108, v26
	v_exp_f32_e32 v55, v55
	v_add_f32_e32 v52, v51, v52
	v_add_f32_e32 v52, v56, v52
	v_add_f32_e32 v52, v63, v52
	v_add_f32_e32 v52, v70, v52
	v_add_f32_e32 v52, v75, v52
	v_add_f32_e32 v52, v42, v52
	v_add_f32_e32 v52, v53, v52
	v_add_f32_e32 v52, v57, v52
	v_add_f32_e32 v52, v59, v52
	v_add_f32_e32 v52, v66, v52
	v_sub_f32_e32 v61, v109, v26
	v_add_f32_e32 v52, v78, v52
	v_exp_f32_e32 v62, v61
	v_sub_f32_e32 v61, v150, v26
	v_add_f32_e32 v52, v82, v52
	v_exp_f32_e32 v68, v61
	v_sub_f32_e32 v61, v151, v26
	v_add_f32_e32 v52, v85, v52
	v_exp_f32_e32 v74, v61
	v_sub_f32_e32 v61, v152, v26
	v_add_f32_e32 v52, v55, v52
	v_exp_f32_e32 v80, v61
	v_sub_f32_e32 v61, v153, v26
	v_add_f32_e32 v52, v62, v52
	v_exp_f32_e32 v88, v61
	v_sub_f32_e32 v61, v154, v26
	v_add_f32_e32 v52, v68, v52
	v_exp_f32_e32 v94, v61
	v_sub_f32_e32 v61, v155, v26
	v_add_f32_e32 v52, v74, v52
	v_exp_f32_e32 v109, v61
	v_sub_f32_e32 v61, v156, v26
	v_add_f32_e32 v52, v80, v52
	v_exp_f32_e32 v64, v61
	v_sub_f32_e32 v61, v157, v26
	v_add_f32_e32 v52, v88, v52
	v_exp_f32_e32 v77, v61
	v_sub_f32_e32 v61, v158, v26
	v_add_f32_e32 v52, v94, v52
	v_exp_f32_e32 v81, v61
	v_sub_f32_e32 v61, v159, v26
	v_add_f32_e32 v52, v109, v52
	v_exp_f32_e32 v83, v61
	v_sub_f32_e32 v61, v160, v26
	v_add_f32_e32 v52, v64, v52
	v_exp_f32_e32 v90, v61
	v_sub_f32_e32 v61, v161, v26
	v_add_f32_e32 v52, v77, v52
	v_exp_f32_e32 v150, v61
	v_sub_f32_e32 v61, v162, v26
	v_add_f32_e32 v52, v81, v52
	v_exp_f32_e32 v152, v61
	v_sub_f32_e32 v61, v163, v26
	v_add_f32_e32 v52, v83, v52
	v_exp_f32_e32 v153, v61
	v_sub_f32_e32 v2, v2, v26
	v_add_f32_e32 v52, v90, v52
	v_exp_f32_e32 v79, v2
	v_sub_f32_e32 v3, v3, v26
	v_add_f32_e32 v52, v150, v52
	v_exp_f32_e32 v86, v3
	v_sub_f32_e32 v3, v4, v26
	v_add_f32_e32 v52, v152, v52
	v_exp_f32_e32 v92, v3
	v_sub_f32_e32 v3, v5, v26
	v_add_f32_e32 v52, v153, v52
	v_exp_f32_e32 v97, v3
	v_sub_f32_e32 v3, v6, v26
	v_add_f32_e32 v2, v79, v52
	v_exp_f32_e32 v151, v3
	v_sub_f32_e32 v3, v7, v26
	v_add_f32_e32 v2, v86, v2
	v_exp_f32_e32 v154, v3
	v_sub_f32_e32 v3, v8, v26
	v_add_f32_e32 v2, v92, v2
	v_exp_f32_e32 v155, v3
	v_sub_f32_e32 v3, v9, v26
	v_add_f32_e32 v2, v97, v2
	v_exp_f32_e32 v156, v3
	v_sub_f32_e32 v3, v10, v26
	v_add_f32_e32 v2, v151, v2
	v_exp_f32_e32 v84, v3
	v_sub_f32_e32 v3, v11, v26
	v_add_f32_e32 v2, v154, v2
	v_exp_f32_e32 v87, v3
	v_sub_f32_e32 v3, v12, v26
	v_add_f32_e32 v2, v155, v2
	v_exp_f32_e32 v89, v3
	v_sub_f32_e32 v3, v13, v26
	v_add_f32_e32 v2, v156, v2
	v_exp_f32_e32 v91, v3
	v_sub_f32_e32 v3, v14, v26
	v_add_f32_e32 v2, v84, v2
	v_exp_f32_e32 v93, v3
	v_sub_f32_e32 v3, v15, v26
	v_add_f32_e32 v2, v87, v2
	v_exp_f32_e32 v95, v3
	v_sub_f32_e32 v3, v16, v26
	v_add_f32_e32 v2, v89, v2
	v_exp_f32_e32 v96, v3
	v_sub_f32_e32 v3, v17, v26
	v_add_f32_e32 v2, v91, v2
	v_exp_f32_e32 v108, v3
	v_sub_f32_e32 v3, v67, v26
	v_add_f32_e32 v2, v93, v2
	v_exp_f32_e32 v61, v3
	v_sub_f32_e32 v3, v50, v26
	v_add_f32_e32 v2, v95, v2
	v_exp_f32_e32 v65, v3
	v_sub_f32_e32 v3, v49, v26
	v_add_f32_e32 v2, v96, v2
	v_exp_f32_e32 v67, v3
	v_sub_f32_e32 v3, v48, v26
	v_add_f32_e32 v2, v108, v2
	v_exp_f32_e32 v69, v3
	v_sub_f32_e32 v3, v47, v26
	v_add_f32_e32 v2, v61, v2
	v_exp_f32_e32 v71, v3
	v_sub_f32_e32 v3, v45, v26
	v_add_f32_e32 v2, v65, v2
	v_exp_f32_e32 v72, v3
	v_sub_f32_e32 v3, v43, v26
	v_add_f32_e32 v2, v67, v2
	v_exp_f32_e32 v73, v3
	v_sub_f32_e32 v3, v40, v26
	v_add_f32_e32 v2, v69, v2
	v_exp_f32_e32 v76, v3
	v_sub_f32_e32 v3, v34, v26
	v_add_f32_e32 v2, v71, v2
	v_exp_f32_e32 v40, v3
	v_sub_f32_e32 v3, v33, v26
	v_add_f32_e32 v2, v72, v2
	v_exp_f32_e32 v43, v3
	v_sub_f32_e32 v3, v32, v26
	v_add_f32_e32 v2, v73, v2
	v_exp_f32_e32 v45, v3
	v_sub_f32_e32 v3, v31, v26
	v_add_f32_e32 v2, v76, v2
	v_exp_f32_e32 v47, v3
	v_sub_f32_e32 v3, v30, v26
	v_add_f32_e32 v2, v40, v2
	v_exp_f32_e32 v48, v3
	v_sub_f32_e32 v3, v29, v26
	v_add_f32_e32 v2, v43, v2
	v_exp_f32_e32 v49, v3
	v_sub_f32_e32 v3, v28, v26
	v_add_f32_e32 v2, v45, v2
	v_exp_f32_e32 v50, v3
	v_sub_f32_e32 v3, v27, v26
	v_add_f32_e32 v2, v47, v2
	v_exp_f32_e32 v52, v3
	v_add_f32_e32 v2, v48, v2
	v_add_f32_e32 v2, v49, v2
	v_add_f32_e32 v2, v50, v2
	v_add_f32_e32 v2, v52, v2
	ds_bpermute_b32 v3, v129, v2
	s_waitcnt lgkmcnt(0)
	v_add_f32_e32 v2, v2, v3
	v_fma_f32 v3, v149, s94, -v26
	v_exp_f32_e32 v3, v3
	s_nop 0
	v_add_f32_e32 v34, v3, v2
	v_cvt_pk_bf16_f32 v2, v18, v19
	v_cvt_pk_bf16_f32 v3, v20, v21
	v_cvt_pk_bf16_f32 v4, v22, v23
	v_cvt_pk_bf16_f32 v5, v24, v25
	ds_read_b128 v[6:9], v107 offset:36864
	s_waitcnt lgkmcnt(0)
	v_mfma_f32_32x32x16_bf16 v[18:33], v[6:9], v[2:5], 0
	ds_read_b128 v[6:9], v106 offset:36864
	v_cvt_pk_bf16_f32 v158, v35, v36
	v_cvt_pk_bf16_f32 v159, v38, v39
	v_cvt_pk_bf16_f32 v160, v44, v54
	v_cvt_pk_bf16_f32 v161, v58, v60
	ds_read_b128 v[162:165], v107 offset:36896
	v_add_u32_e32 v35, v137, v131
	s_waitcnt lgkmcnt(0)
	v_mfma_f32_32x32x16_bf16 v[18:33], v[162:165], v[158:161], v[18:33]
	ds_read_b128 v[162:165], v106 offset:36896
	v_cvt_pk_bf16_f32 v36, v37, v41
	v_cvt_pk_bf16_f32 v37, v46, v51
	v_cvt_pk_bf16_f32 v38, v56, v63
	v_cvt_pk_bf16_f32 v39, v70, v75
	v_add_u32_e32 v44, v137, v132
	v_mfma_f32_32x32x16_bf16 v[2:17], v[6:9], v[2:5], 0
	s_waitcnt lgkmcnt(0)
	v_mfma_f32_32x32x16_bf16 v[2:17], v[162:165], v[158:161], v[2:17]
	ds_read_b128 v[178:181], v105 offset:36864
	ds_read_b128 v[182:185], v104 offset:36864
	ds_read_b128 v[186:189], v105 offset:36896
	s_waitcnt lgkmcnt(2)
	v_mfma_f32_32x32x16_bf16 v[18:33], v[178:181], v[36:39], v[18:33]
	ds_read_b128 v[190:193], v104 offset:36896
	s_waitcnt lgkmcnt(2)
	v_mfma_f32_32x32x16_bf16 v[2:17], v[182:185], v[36:39], v[2:17]
	v_cvt_pk_bf16_f32 v36, v42, v53
	v_cvt_pk_bf16_f32 v37, v57, v59
	v_cvt_pk_bf16_f32 v38, v66, v78
	v_cvt_pk_bf16_f32 v39, v82, v85
	ds_read_b128 v[178:181], v103 offset:36864
	s_waitcnt lgkmcnt(2)
	v_mfma_f32_32x32x16_bf16 v[18:33], v[186:189], v[36:39], v[18:33]
	ds_read_b128 v[182:185], v102 offset:36864
	s_waitcnt lgkmcnt(2)
	v_mfma_f32_32x32x16_bf16 v[2:17], v[190:193], v[36:39], v[2:17]
	v_cvt_pk_bf16_f32 v36, v55, v62
	v_cvt_pk_bf16_f32 v37, v68, v74
	v_cvt_pk_bf16_f32 v38, v80, v88
	v_cvt_pk_bf16_f32 v39, v94, v109
	ds_read_b128 v[186:189], v103 offset:36896
	s_waitcnt lgkmcnt(2)
	v_mfma_f32_32x32x16_bf16 v[18:33], v[178:181], v[36:39], v[18:33]
	ds_read_b128 v[190:193], v102 offset:36896
	s_waitcnt lgkmcnt(2)
	v_mfma_f32_32x32x16_bf16 v[2:17], v[182:185], v[36:39], v[2:17]
	v_cvt_pk_bf16_f32 v36, v64, v77
	v_cvt_pk_bf16_f32 v37, v81, v83
	v_cvt_pk_bf16_f32 v38, v90, v150
	v_cvt_pk_bf16_f32 v39, v152, v153
	ds_read_b128 v[178:181], v101 offset:36864
	s_waitcnt lgkmcnt(2)
	v_mfma_f32_32x32x16_bf16 v[18:33], v[186:189], v[36:39], v[18:33]
	ds_read_b128 v[182:185], v100 offset:36864
	s_waitcnt lgkmcnt(2)
	v_mfma_f32_32x32x16_bf16 v[2:17], v[190:193], v[36:39], v[2:17]
	v_cvt_pk_bf16_f32 v36, v79, v86
	v_cvt_pk_bf16_f32 v37, v92, v97
	v_cvt_pk_bf16_f32 v38, v151, v154
	v_cvt_pk_bf16_f32 v39, v155, v156
	ds_read_b128 v[186:189], v101 offset:36896
	s_waitcnt lgkmcnt(2)
	v_mfma_f32_32x32x16_bf16 v[18:33], v[178:181], v[36:39], v[18:33]
	ds_read_b128 v[190:193], v100 offset:36896
	s_waitcnt lgkmcnt(2)
	v_mfma_f32_32x32x16_bf16 v[2:17], v[182:185], v[36:39], v[2:17]
	v_cvt_pk_bf16_f32 v36, v84, v87
	v_cvt_pk_bf16_f32 v37, v89, v91
	v_cvt_pk_bf16_f32 v38, v93, v95
	v_cvt_pk_bf16_f32 v39, v96, v108
	ds_read_b128 v[178:181], v35 offset:36864
	s_waitcnt lgkmcnt(2)
	v_mfma_f32_32x32x16_bf16 v[18:33], v[186:189], v[36:39], v[18:33]
	ds_read_b128 v[182:185], v44 offset:36864
	s_waitcnt lgkmcnt(2)
	v_mfma_f32_32x32x16_bf16 v[2:17], v[190:193], v[36:39], v[2:17]
	v_cvt_pk_bf16_f32 v36, v61, v65
	v_cvt_pk_bf16_f32 v37, v67, v69
	v_cvt_pk_bf16_f32 v38, v71, v72
	v_cvt_pk_bf16_f32 v39, v73, v76
	ds_read_b128 v[186:189], v35 offset:36896
	s_waitcnt lgkmcnt(2)
	v_mfma_f32_32x32x16_bf16 v[18:33], v[178:181], v[36:39], v[18:33]
	ds_read_b128 v[190:193], v44 offset:36896
	s_waitcnt lgkmcnt(2)
	v_mfma_f32_32x32x16_bf16 v[2:17], v[182:185], v[36:39], v[2:17]
	v_cvt_pk_bf16_f32 v36, v40, v43
	v_cvt_pk_bf16_f32 v37, v45, v47
	v_cvt_pk_bf16_f32 v38, v48, v49
	v_cvt_pk_bf16_f32 v39, v50, v52
	v_div_scale_f32 v35, s[48:49], v34, v34, 1.0
	s_waitcnt lgkmcnt(1)
	v_mfma_f32_32x32x16_bf16 v[18:33], v[186:189], v[36:39], v[18:33]
	s_waitcnt lgkmcnt(0)
	v_mfma_f32_32x32x16_bf16 v[2:17], v[190:193], v[36:39], v[2:17]
	v_rcp_f32_e32 v36, v35
	s_nop 0
	v_fma_f32 v37, -v35, v36, 1.0
	v_fmac_f32_e32 v36, v37, v36
	v_div_scale_f32 v37, vcc, 1.0, v34, 1.0
	v_mul_f32_e32 v38, v37, v36
	v_fma_f32 v39, -v35, v38, v37
	v_fmac_f32_e32 v38, v39, v36
	v_fma_f32 v35, -v35, v38, v37
	v_div_fmas_f32 v35, v35, v36, v38
	v_div_fixup_f32 v36, v35, v34, 1.0
	v_lshlrev_b64 v[34:35], 11, v[98:99]
	v_bfe_u32 v204, v0, 5, 1
	v_lshl_add_u64 v[34:35], v[126:127], 0, v[34:35]
	v_lshlrev_b32_e32 v204, 3, v204
	v_mov_b32_e32 v205, 0
	v_mul_f32_e32 v18, v18, v36
	v_mul_f32_e32 v19, v19, v36
	v_cvt_pk_bf16_f32 v18, v18, v19
	v_mul_f32_e32 v19, v20, v36
	v_mul_f32_e32 v20, v21, v36
	v_cvt_pk_bf16_f32 v19, v19, v20
	v_mul_f32_e32 v20, v22, v36
	v_mul_f32_e32 v21, v23, v36
	v_cvt_pk_bf16_f32 v20, v20, v21
	v_mul_f32_e32 v21, v24, v36
	v_mul_f32_e32 v22, v25, v36
	v_cvt_pk_bf16_f32 v21, v21, v22
	v_lshl_add_u64 v[34:35], v[34:35], 0, v[204:205]
	v_mul_f32_e32 v26, v26, v36
	v_mul_f32_e32 v27, v27, v36
	v_cvt_pk_bf16_f32 v26, v26, v27
	v_mul_f32_e32 v27, v28, v36
	v_mul_f32_e32 v28, v29, v36
	v_cvt_pk_bf16_f32 v27, v27, v28
	v_mul_f32_e32 v28, v30, v36
	v_mul_f32_e32 v29, v31, v36
	v_cvt_pk_bf16_f32 v28, v28, v29
	v_mul_f32_e32 v29, v32, v36
	v_mul_f32_e32 v30, v33, v36
	v_cvt_pk_bf16_f32 v29, v29, v30
	v_permlane32_swap_b32 v18, v20
	v_permlane32_swap_b32 v19, v21
	global_store_dwordx4 v[34:35], v[18:21], off
	v_permlane32_swap_b32 v26, v28
	v_permlane32_swap_b32 v27, v29
	global_store_dwordx4 v[34:35], v[26:29], off offset:32
	v_mul_f32_e32 v2, v2, v36
	v_mul_f32_e32 v3, v3, v36
	v_cvt_pk_bf16_f32 v2, v2, v3
	v_mul_f32_e32 v3, v4, v36
	v_mul_f32_e32 v4, v5, v36
	v_cvt_pk_bf16_f32 v3, v3, v4
	v_mul_f32_e32 v4, v6, v36
	v_mul_f32_e32 v5, v7, v36
	v_cvt_pk_bf16_f32 v4, v4, v5
	v_mul_f32_e32 v5, v8, v36
	v_mul_f32_e32 v6, v9, v36
	v_cvt_pk_bf16_f32 v5, v5, v6
	v_mul_f32_e32 v10, v10, v36
	v_mul_f32_e32 v11, v11, v36
	v_cvt_pk_bf16_f32 v10, v10, v11
	v_mul_f32_e32 v11, v12, v36
	v_mul_f32_e32 v12, v13, v36
	v_cvt_pk_bf16_f32 v11, v11, v12
	v_mul_f32_e32 v12, v14, v36
	v_mul_f32_e32 v13, v15, v36
	v_cvt_pk_bf16_f32 v12, v12, v13
	v_mul_f32_e32 v13, v16, v36
	v_mul_f32_e32 v14, v17, v36
	v_cvt_pk_bf16_f32 v13, v13, v14
	v_permlane32_swap_b32 v2, v4
	v_permlane32_swap_b32 v3, v5
	global_store_dwordx4 v[34:35], v[2:5], off offset:64
	v_permlane32_swap_b32 v10, v12
	v_permlane32_swap_b32 v11, v13
	global_store_dwordx4 v[34:35], v[10:13], off offset:96
	s_cbranch_scc0 .LBB0_821
